# HK2 + attention loop-edge trim: uniform-branch mask fed from the compares, redundant canonicalising max dropped
# baseline (speedup 1.0000x reference)
;     __device__ bool next(int i, Unit& u) const { if (i != 0) return false; return so.next(round, u); }
;     __device__ __forceinline__ bool next(int i, Unit& u) const { if (i > 0 || !on) return false; u.pm = pm; u.pn = 0; return true; }
; #define PG8_STAGE(bufoff, gbase, voff) do { _Pragma("unroll") for (int _i = 0; _i < 2; ++_i) \
;         __builtin_amdgcn_global_load_lds((const unsigned*)((const char*)(gbase) + (voff)[_i]), (PG8_LAS unsigned*)(lds + (bufoff) + ldsw + _i * 8192), 16, 0, 0); } while (0)
; #define PG8_LDA(dst, b, h) do { _Pragma("unroll") for (int m = 0; m < 4; ++m) _Pragma("unroll") for (int k = 0; k < 2; ++k) dst[m][k] = *(const PG8_LAS bf16x8*)(lds + PG8_SA(b, h) + aoff + m * 2048 + k * 1024); } while (0)
; #define PG8_WAIT_V(n) asm volatile("s_waitcnt vmcnt(" #n ")" ::: "memory")
; template <class Epi, class Sched, bool ALIGN_EPI = false, bool SP2 = false, bool MIDHOOK = false>
; __device__ __forceinline__ void gemm_phase(PG8_LAS unsigned char* lds, const Gemm g, const Sched& S, const Epi& E) {
;     ...
;         const bool has_next = S.next(ui + 1, nxt);
;         const char* nA = has_next ? (const char*)g.A + (size_t)nxt.pm * tstep : cA; const char* nB = has_next ? (const char*)g.Bt + (size_t)nxt.pn * tstep : cB;
;         for (int t = 0; t < nt; t += 2) {
;             if constexpr (MIDHOOK) { if (t == nt / 2) E.mid(acc, cur, wr, wc, fr, fq); }
;             const bool last = (t == nt - 2);
;             const char* a1 = cA + (size_t)(t + 1) * kstep;
;             const char* a2 = last ? nA : cA + (size_t)(t + 2) * kstep; const char* b2 = last ? nB : cB + (size_t)(t + 2) * kstep;
;             const char* a3 = a2 + kstep; const char* b3 = b2 + kstep;
;             if (last && has_next) S.a_ready(nxt);
;             if constexpr (SP2) {
;             PG8_LDB(B0, 0, 0); PG8_LDB(B1, 0, 1); PG8_SCHED; PG8_LDA(At, 0, 0); PG8_STAGE(PG8_SA(1, 1), a1 + hstep, voffA);
;             PG8_WAIT_V(8); PG8_WAIT_L(0); PG8_BAR; PG8_MMA(0, 0, At, B0); PG8_MMA(0, 1, At, B1); PG8_BAR; PG8_SCHED;
;     ...
; #pragma unroll
;         for (int a = 0; a < 2; ++a)
; #pragma unroll
;             for (int b = 0; b < 2; ++b)
; #pragma unroll
;                 for (int m = 0; m < 4; ++m)
; #pragma unroll
;                     for (int n = 0; n < 2; ++n) acc[a][b][m][n] = (f32x4){0.f, 0.f, 0.f, 0.f};
;         cur = nxt; cA = nA; cB = nB; ++ui;
.LBB0_3840:
	s_ashr_i32 s19, s18, 31
	s_lshl_b64 s[20:21], s[18:19], 19
	s_add_u32 s20, s68, s20
	s_addc_u32 s21, s69, s21
	s_and_b64 s[22:23], s[0:1], exec
	s_cselect_b32 s19, s21, s25
	s_cselect_b32 s46, s20, s24
	s_ashr_i32 s17, s16, 31
	s_lshl_b64 s[22:23], s[16:17], 19
	v_readlane_b32 s30, v243, 24
	v_readlane_b32 s31, v243, 25
	s_add_u32 s22, s30, s22
	s_addc_u32 s23, s31, s23
	s_and_b64 s[30:31], s[0:1], exec
	v_mov_b32_e32 v2, v0
	v_mov_b32_e32 v3, v0
	s_cselect_b32 s17, s23, s29
	s_cselect_b32 s47, s22, s28
	s_add_u32 s48, s28, 0x100
	v_mov_b32_e32 v1, v0
	v_mov_b64_e32 v[6:7], v[2:3]
	v_mov_b64_e32 v[10:11], v[2:3]
	v_mov_b64_e32 v[22:23], v[2:3]
	v_mov_b64_e32 v[26:27], v[2:3]
	v_mov_b64_e32 v[38:39], v[2:3]
	v_mov_b64_e32 v[42:43], v[2:3]
	v_mov_b64_e32 v[54:55], v[2:3]
	v_mov_b64_e32 v[58:59], v[2:3]
	v_mov_b64_e32 v[14:15], v[2:3]
	v_mov_b64_e32 v[18:19], v[2:3]
	v_mov_b64_e32 v[30:31], v[2:3]
	v_mov_b64_e32 v[34:35], v[2:3]
	v_mov_b64_e32 v[46:47], v[2:3]
	v_mov_b64_e32 v[50:51], v[2:3]
	v_mov_b64_e32 v[62:63], v[2:3]
	v_mov_b64_e32 v[66:67], v[2:3]
	v_mov_b64_e32 v[70:71], v[2:3]
	v_mov_b64_e32 v[74:75], v[2:3]
	v_mov_b64_e32 v[86:87], v[2:3]
	v_mov_b64_e32 v[90:91], v[2:3]
	v_mov_b64_e32 v[102:103], v[2:3]
	v_mov_b64_e32 v[106:107], v[2:3]
	v_mov_b64_e32 v[118:119], v[2:3]
	v_mov_b64_e32 v[122:123], v[2:3]
	v_mov_b64_e32 v[78:79], v[2:3]
	v_mov_b64_e32 v[82:83], v[2:3]
	v_mov_b64_e32 v[94:95], v[2:3]
	v_mov_b64_e32 v[98:99], v[2:3]
	v_mov_b64_e32 v[110:111], v[2:3]
	v_mov_b64_e32 v[114:115], v[2:3]
	v_mov_b64_e32 v[126:127], v[2:3]
	v_mov_b64_e32 v[130:131], v[2:3]
	v_lshl_add_u32 v204, s26, 8, v223
	v_lshl_add_u32 v206, s27, 8, v225
	v_lshl_add_u64 v[208:209], s[24:25], 0, v[196:197]
	v_lshl_add_u64 v[210:211], s[24:25], 0, v[198:199]
	s_addc_u32 s49, s29, 0
	s_mov_b32 s50, -2
	s_mov_b64 s[26:27], 0
	v_mov_b64_e32 v[4:5], v[0:1]
	v_mov_b64_e32 v[8:9], v[0:1]
	v_mov_b64_e32 v[20:21], v[0:1]
	v_mov_b64_e32 v[24:25], v[0:1]
	v_mov_b64_e32 v[36:37], v[0:1]
	v_mov_b64_e32 v[40:41], v[0:1]
	v_mov_b64_e32 v[52:53], v[0:1]
	v_mov_b64_e32 v[56:57], v[0:1]
	v_mov_b64_e32 v[12:13], v[0:1]
	v_mov_b64_e32 v[16:17], v[0:1]
	v_mov_b64_e32 v[28:29], v[0:1]
	v_mov_b64_e32 v[32:33], v[0:1]
	v_mov_b64_e32 v[44:45], v[0:1]
	v_mov_b64_e32 v[48:49], v[0:1]
	v_mov_b64_e32 v[60:61], v[0:1]
	v_mov_b64_e32 v[64:65], v[0:1]
	v_mov_b64_e32 v[68:69], v[0:1]
	v_mov_b64_e32 v[72:73], v[0:1]
	v_mov_b64_e32 v[84:85], v[0:1]
	v_mov_b64_e32 v[88:89], v[0:1]
	v_mov_b64_e32 v[100:101], v[0:1]
	v_mov_b64_e32 v[104:105], v[0:1]
	v_mov_b64_e32 v[116:117], v[0:1]
	v_mov_b64_e32 v[120:121], v[0:1]
	v_mov_b64_e32 v[76:77], v[0:1]
	v_mov_b64_e32 v[80:81], v[0:1]
	v_mov_b64_e32 v[92:93], v[0:1]
	v_mov_b64_e32 v[96:97], v[0:1]
	v_mov_b64_e32 v[108:109], v[0:1]
	v_mov_b64_e32 v[112:113], v[0:1]
	v_mov_b64_e32 v[124:125], v[0:1]
	v_mov_b64_e32 v[128:129], v[0:1]
	s_branch .LBB0_3842
	s_nop 0
	s_nop 0
	s_nop 0
	s_nop 0
.LBB0_3841:
	v_add_u32_e32 v1, s44, v224
	ds_read_b128 v[132:135], v1
	ds_read_b128 v[136:139], v1 offset:1024
	ds_read_b128 v[140:143], v1 offset:2048
	ds_read_b128 v[144:147], v1 offset:3072
	v_add_u32_e32 v1, s45, v224
	s_add_u32 s28, s24, s26
	ds_read_b128 v[148:151], v1
	ds_read_b128 v[152:155], v1 offset:1024
	ds_read_b128 v[156:159], v1 offset:2048
	ds_read_b128 v[160:163], v1 offset:3072
	s_addc_u32 s29, s25, s27
	s_add_u32 s28, s28, 0x100
	s_addc_u32 s29, s29, 0
	s_add_u32 s51, s48, s26
	s_addc_u32 s52, s49, s27
	s_cmpk_eq_i32 s26, 0x700
	s_cselect_b32 s31, s19, s29
	s_cselect_b32 s30, s46, s28
	s_cselect_b32 s29, s17, s52
	s_cselect_b32 s28, s47, s51
	v_lshl_add_u64 v[2:3], v[208:209], 0, s[26:27]
	s_add_i32 m0, s35, 0xc000
	ds_read_b128 v[164:167], v226
	ds_read_b128 v[168:171], v226 offset:1024
	ds_read_b128 v[172:175], v226 offset:2048
	ds_read_b128 v[176:179], v226 offset:3072
	ds_read_b128 v[180:183], v226 offset:4096
	ds_read_b128 v[184:187], v226 offset:5120
	ds_read_b128 v[212:215], v226 offset:6144
	ds_read_b128 v[216:219], v226 offset:7168
	global_load_lds_dwordx4 v[2:3], off
	v_lshl_add_u64 v[2:3], v[210:211], 0, s[26:27]
	s_add_i32 m0, s35, 0xe000
	s_nop 0
	global_load_lds_dwordx4 v[2:3], off
	s_waitcnt vmcnt(8)
	s_waitcnt lgkmcnt(0)
	s_barrier
	s_setprio 1
	s_waitcnt lgkmcnt(0)
	v_mfma_f32_16x16x32_bf16 v[128:131], v[132:135], v[164:167], v[128:131]
	v_mfma_f32_16x16x32_bf16 v[124:127], v[140:143], v[164:167], v[124:127]
	v_mfma_f32_16x16x32_bf16 v[112:115], v[132:135], v[172:175], v[112:115]
	v_mfma_f32_16x16x32_bf16 v[108:111], v[140:143], v[172:175], v[108:111]
	v_mfma_f32_16x16x32_bf16 v[96:99], v[132:135], v[180:183], v[96:99]
	v_mfma_f32_16x16x32_bf16 v[92:95], v[140:143], v[180:183], v[92:95]
	v_mfma_f32_16x16x32_bf16 v[80:83], v[132:135], v[212:215], v[80:83]
	v_mfma_f32_16x16x32_bf16 v[76:79], v[140:143], v[212:215], v[76:79]
	v_mfma_f32_16x16x32_bf16 v[128:131], v[136:139], v[168:171], v[128:131]
	v_mfma_f32_16x16x32_bf16 v[124:127], v[144:147], v[168:171], v[124:127]
	v_mfma_f32_16x16x32_bf16 v[112:115], v[136:139], v[176:179], v[112:115]
	v_mfma_f32_16x16x32_bf16 v[108:111], v[144:147], v[176:179], v[108:111]
	v_mfma_f32_16x16x32_bf16 v[96:99], v[136:139], v[184:187], v[96:99]
	v_mfma_f32_16x16x32_bf16 v[92:95], v[144:147], v[184:187], v[92:95]
	v_mfma_f32_16x16x32_bf16 v[80:83], v[136:139], v[216:219], v[80:83]
	v_mfma_f32_16x16x32_bf16 v[76:79], v[144:147], v[216:219], v[76:79]
	s_setprio 0
	s_setprio 1
	v_mfma_f32_16x16x32_bf16 v[120:123], v[148:151], v[164:167], v[120:123]
	v_mfma_f32_16x16x32_bf16 v[116:119], v[156:159], v[164:167], v[116:119]
	v_mfma_f32_16x16x32_bf16 v[104:107], v[148:151], v[172:175], v[104:107]
	v_mfma_f32_16x16x32_bf16 v[100:103], v[156:159], v[172:175], v[100:103]
	v_mfma_f32_16x16x32_bf16 v[88:91], v[148:151], v[180:183], v[88:91]
	v_mfma_f32_16x16x32_bf16 v[84:87], v[156:159], v[180:183], v[84:87]
	v_mfma_f32_16x16x32_bf16 v[72:75], v[148:151], v[212:215], v[72:75]
	v_mfma_f32_16x16x32_bf16 v[68:71], v[156:159], v[212:215], v[68:71]
	v_mfma_f32_16x16x32_bf16 v[120:123], v[152:155], v[168:171], v[120:123]
	v_mfma_f32_16x16x32_bf16 v[116:119], v[160:163], v[168:171], v[116:119]
	v_mfma_f32_16x16x32_bf16 v[104:107], v[152:155], v[176:179], v[104:107]
	v_mfma_f32_16x16x32_bf16 v[100:103], v[160:163], v[176:179], v[100:103]
	v_mfma_f32_16x16x32_bf16 v[88:91], v[152:155], v[184:187], v[88:91]
	v_mfma_f32_16x16x32_bf16 v[84:87], v[160:163], v[184:187], v[84:87]
	v_mfma_f32_16x16x32_bf16 v[72:75], v[152:155], v[216:219], v[72:75]
	v_mfma_f32_16x16x32_bf16 v[68:71], v[160:163], v[216:219], v[68:71]
	s_setprio 0
	s_barrier
; #define PG8_STAGE(bufoff, gbase, voff) do { _Pragma("unroll") for (int _i = 0; _i < 2; ++_i) \
;         __builtin_amdgcn_global_load_lds((const unsigned*)((const char*)(gbase) + (voff)[_i]), (PG8_LAS unsigned*)(lds + (bufoff) + ldsw + _i * 8192), 16, 0, 0); } while (0)
; #define PG8_LDA(dst, b, h) do { _Pragma("unroll") for (int m = 0; m < 4; ++m) _Pragma("unroll") for (int k = 0; k < 2; ++k) dst[m][k] = *(const PG8_LAS bf16x8*)(lds + PG8_SA(b, h) + aoff + m * 2048 + k * 1024); } while (0)
; #define PG8_LDB(dst, b, h) do { _Pragma("unroll") for (int n = 0; n < 2; ++n) _Pragma("unroll") for (int k = 0; k < 2; ++k) dst[n][k] = *(const PG8_LAS bf16x8*)(lds + PG8_SB(b, h) + boff + n * 2048 + k * 1024); } while (0)
; #define PG8_MMA(ai, bj, At, Bt) do { __builtin_amdgcn_s_setprio(1); _Pragma("unroll") for (int m = 0; m < 4; ++m) _Pragma("unroll") for (int n = 0; n < 2; ++n) _Pragma("unroll") for (int k = 0; k < 2; ++k) \
;         acc[ai][bj][m][n] = __builtin_amdgcn_mfma_f32_16x16x32_bf16(Bt[n][k], At[m][k], acc[ai][bj][m][n], 0, 0, 0); __builtin_amdgcn_s_setprio(0); } while (0)
; #define PG8_WAIT_V(n) asm volatile("s_waitcnt vmcnt(" #n ")" ::: "memory")
; #define PG8_WAIT_L(n) asm volatile("s_waitcnt lgkmcnt(" #n ")" ::: "memory")
; #define PG8_BAR __builtin_amdgcn_s_barrier()
; #define PG8_SCHED __builtin_amdgcn_sched_barrier(0)
; template <class Epi, class Sched, bool ALIGN_EPI = false, bool SP2 = false, bool MIDHOOK = false>
; __device__ __forceinline__ void gemm_phase(PG8_LAS unsigned char* lds, const Gemm g, const Sched& S, const Epi& E) {
;     ...
;             PG8_LDA(At, 0, 1); PG8_STAGE(PG8_SB(0, 0), b2, voffB); PG8_STAGE(PG8_SB(0, 1), b2 + hstep, voffB); PG8_STAGE(PG8_SA(0, 0), a2, voffA);
;             PG8_WAIT_V(8); PG8_WAIT_L(0); PG8_BAR; PG8_MMA(1, 0, At, B0); PG8_MMA(1, 1, At, B1); PG8_BAR; PG8_SCHED;
;             PG8_LDB(B0, 1, 0); PG8_LDB(B1, 1, 1); PG8_SCHED; PG8_LDA(At, 1, 0); PG8_STAGE(PG8_SA(0, 1), a2 + hstep, voffA);
;             PG8_WAIT_V(8); PG8_WAIT_L(0); PG8_BAR; PG8_MMA(0, 0, At, B0); PG8_MMA(0, 1, At, B1); PG8_BAR; PG8_SCHED;
	s_add_i32 s51, s44, s34
	v_lshl_add_u64 v[228:229], s[28:29], 0, v[190:191]
	s_mov_b32 m0, s51
	ds_read_b128 v[164:167], v226 offset:16384
	ds_read_b128 v[168:171], v226 offset:17408
	ds_read_b128 v[172:175], v226 offset:18432
	ds_read_b128 v[176:179], v226 offset:19456
	ds_read_b128 v[180:183], v226 offset:20480
	ds_read_b128 v[184:187], v226 offset:21504
	ds_read_b128 v[212:215], v226 offset:22528
	ds_read_b128 v[216:219], v226 offset:23552
	global_load_lds_dwordx4 v[228:229], off
	s_add_i32 m0, s51, 0x2000
	s_add_u32 s52, s28, 0x40000
	v_lshl_add_u64 v[230:231], s[28:29], 0, v[194:195]
	s_addc_u32 s53, s29, 0
	s_add_i32 s51, s45, s34
	global_load_lds_dwordx4 v[230:231], off
	v_lshl_add_u64 v[2:3], s[52:53], 0, v[190:191]
	s_mov_b32 m0, s51
	v_lshl_add_u64 v[232:233], s[30:31], 0, v[188:189]
	global_load_lds_dwordx4 v[2:3], off
	v_lshl_add_u64 v[2:3], s[52:53], 0, v[194:195]
	s_add_i32 m0, s51, 0x2000
	v_lshl_add_u64 v[234:235], s[30:31], 0, v[192:193]
	global_load_lds_dwordx4 v[2:3], off
	s_mov_b32 m0, s35
	s_nop 0
	global_load_lds_dwordx4 v[232:233], off
	s_mov_b32 m0, s36
	s_nop 0
	global_load_lds_dwordx4 v[234:235], off
	s_waitcnt vmcnt(8)
	s_waitcnt lgkmcnt(0)
	s_barrier
	s_setprio 1
	s_waitcnt lgkmcnt(0)
	v_mfma_f32_16x16x32_bf16 v[64:67], v[132:135], v[164:167], v[64:67]
	v_mfma_f32_16x16x32_bf16 v[60:63], v[140:143], v[164:167], v[60:63]
	v_mfma_f32_16x16x32_bf16 v[48:51], v[132:135], v[172:175], v[48:51]
	v_mfma_f32_16x16x32_bf16 v[44:47], v[140:143], v[172:175], v[44:47]
	v_mfma_f32_16x16x32_bf16 v[32:35], v[132:135], v[180:183], v[32:35]
	v_mfma_f32_16x16x32_bf16 v[28:31], v[140:143], v[180:183], v[28:31]
	v_mfma_f32_16x16x32_bf16 v[16:19], v[132:135], v[212:215], v[16:19]
	v_mfma_f32_16x16x32_bf16 v[12:15], v[140:143], v[212:215], v[12:15]
	v_mfma_f32_16x16x32_bf16 v[64:67], v[136:139], v[168:171], v[64:67]
	v_mfma_f32_16x16x32_bf16 v[60:63], v[144:147], v[168:171], v[60:63]
	v_mfma_f32_16x16x32_bf16 v[48:51], v[136:139], v[176:179], v[48:51]
	v_mfma_f32_16x16x32_bf16 v[44:47], v[144:147], v[176:179], v[44:47]
	v_mfma_f32_16x16x32_bf16 v[32:35], v[136:139], v[184:187], v[32:35]
	v_mfma_f32_16x16x32_bf16 v[28:31], v[144:147], v[184:187], v[28:31]
	v_mfma_f32_16x16x32_bf16 v[16:19], v[136:139], v[216:219], v[16:19]
	v_mfma_f32_16x16x32_bf16 v[12:15], v[144:147], v[216:219], v[12:15]
	s_setprio 0
	s_setprio 1
	v_mfma_f32_16x16x32_bf16 v[56:59], v[148:151], v[164:167], v[56:59]
	v_mfma_f32_16x16x32_bf16 v[52:55], v[156:159], v[164:167], v[52:55]
	v_mfma_f32_16x16x32_bf16 v[40:43], v[148:151], v[172:175], v[40:43]
	v_mfma_f32_16x16x32_bf16 v[36:39], v[156:159], v[172:175], v[36:39]
	v_mfma_f32_16x16x32_bf16 v[24:27], v[148:151], v[180:183], v[24:27]
	v_mfma_f32_16x16x32_bf16 v[20:23], v[156:159], v[180:183], v[20:23]
	v_mfma_f32_16x16x32_bf16 v[8:11], v[148:151], v[212:215], v[8:11]
	v_mfma_f32_16x16x32_bf16 v[2:5], v[156:159], v[212:215], v[4:7]
	v_mfma_f32_16x16x32_bf16 v[56:59], v[152:155], v[168:171], v[56:59]
	v_mfma_f32_16x16x32_bf16 v[52:55], v[160:163], v[168:171], v[52:55]
	v_mfma_f32_16x16x32_bf16 v[40:43], v[152:155], v[176:179], v[40:43]
	v_mfma_f32_16x16x32_bf16 v[36:39], v[160:163], v[176:179], v[36:39]
	v_mfma_f32_16x16x32_bf16 v[24:27], v[152:155], v[184:187], v[24:27]
	v_mfma_f32_16x16x32_bf16 v[20:23], v[160:163], v[184:187], v[20:23]
	v_mfma_f32_16x16x32_bf16 v[8:11], v[152:155], v[216:219], v[8:11]
	v_mfma_f32_16x16x32_bf16 v[2:5], v[160:163], v[216:219], v[2:5]
	s_setprio 0
	s_barrier
	s_add_i32 s51, 0, 0x18000
	v_add_u32_e32 v1, s51, v224
	s_add_i32 s52, 0, 0x1c000
	ds_read_b128 v[132:135], v1
	ds_read_b128 v[136:139], v1 offset:1024
	ds_read_b128 v[140:143], v1 offset:2048
	ds_read_b128 v[144:147], v1 offset:3072
	v_add_u32_e32 v1, s52, v224
	ds_read_b128 v[148:151], v1
	ds_read_b128 v[152:155], v1 offset:1024
	ds_read_b128 v[156:159], v1 offset:2048
	ds_read_b128 v[160:163], v1 offset:3072
	s_add_u32 s30, s30, 0x40000
	s_addc_u32 s31, s31, 0
	s_mov_b32 m0, s37
	v_lshl_add_u64 v[6:7], s[30:31], 0, v[188:189]
	ds_read_b128 v[164:167], v226 offset:32768
	ds_read_b128 v[168:171], v226 offset:33792
	ds_read_b128 v[172:175], v226 offset:34816
	ds_read_b128 v[176:179], v226 offset:35840
	ds_read_b128 v[180:183], v226 offset:36864
	ds_read_b128 v[184:187], v226 offset:37888
	ds_read_b128 v[212:215], v226 offset:38912
	ds_read_b128 v[216:219], v226 offset:39936
	global_load_lds_dwordx4 v[6:7], off
	v_lshl_add_u64 v[6:7], s[30:31], 0, v[192:193]
	s_mov_b32 m0, s38
	s_nop 0
	global_load_lds_dwordx4 v[6:7], off
	s_waitcnt vmcnt(8)
	s_waitcnt lgkmcnt(0)
	s_barrier
; #define PG8_STAGE(bufoff, gbase, voff) do { _Pragma("unroll") for (int _i = 0; _i < 2; ++_i) \
;         __builtin_amdgcn_global_load_lds((const unsigned*)((const char*)(gbase) + (voff)[_i]), (PG8_LAS unsigned*)(lds + (bufoff) + ldsw + _i * 8192), 16, 0, 0); } while (0)
; #define PG8_LDA(dst, b, h) do { _Pragma("unroll") for (int m = 0; m < 4; ++m) _Pragma("unroll") for (int k = 0; k < 2; ++k) dst[m][k] = *(const PG8_LAS bf16x8*)(lds + PG8_SA(b, h) + aoff + m * 2048 + k * 1024); } while (0)
; #define PG8_MMA(ai, bj, At, Bt) do { __builtin_amdgcn_s_setprio(1); _Pragma("unroll") for (int m = 0; m < 4; ++m) _Pragma("unroll") for (int n = 0; n < 2; ++n) _Pragma("unroll") for (int k = 0; k < 2; ++k) \
;         acc[ai][bj][m][n] = __builtin_amdgcn_mfma_f32_16x16x32_bf16(Bt[n][k], At[m][k], acc[ai][bj][m][n], 0, 0, 0); __builtin_amdgcn_s_setprio(0); } while (0)
; #define PG8_WAIT_V(n) asm volatile("s_waitcnt vmcnt(" #n ")" ::: "memory")
; #define PG8_WAIT_L(n) asm volatile("s_waitcnt lgkmcnt(" #n ")" ::: "memory")
; #define PG8_BAR __builtin_amdgcn_s_barrier()
; #define PG8_SCHED __builtin_amdgcn_sched_barrier(0)
; template <class Epi, class Sched, bool ALIGN_EPI = false, bool SP2 = false, bool MIDHOOK = false>
; __device__ __forceinline__ void gemm_phase(PG8_LAS unsigned char* lds, const Gemm g, const Sched& S, const Epi& E) {
;     ...
;         for (int t = 0; t < nt; t += 2) {
;     ...
;             PG8_WAIT_V(8); PG8_WAIT_L(0); PG8_BAR; PG8_MMA(0, 0, At, B0); PG8_MMA(0, 1, At, B1); PG8_BAR; PG8_SCHED;
;             PG8_LDA(At, 1, 1); PG8_STAGE(PG8_SB(1, 0), b3, voffB); PG8_STAGE(PG8_SB(1, 1), b3 + hstep, voffB); PG8_STAGE(PG8_SA(1, 0), a3, voffA);
;             PG8_WAIT_V(8); PG8_WAIT_L(0); PG8_BAR; PG8_MMA(1, 0, At, B0); PG8_MMA(1, 1, At, B1); PG8_BAR; PG8_SCHED;
	s_setprio 1
	s_waitcnt lgkmcnt(0)
	v_mfma_f32_16x16x32_bf16 v[128:131], v[132:135], v[164:167], v[128:131]
	v_mfma_f32_16x16x32_bf16 v[124:127], v[140:143], v[164:167], v[124:127]
	v_mfma_f32_16x16x32_bf16 v[112:115], v[132:135], v[172:175], v[112:115]
	v_mfma_f32_16x16x32_bf16 v[108:111], v[140:143], v[172:175], v[108:111]
	v_mfma_f32_16x16x32_bf16 v[96:99], v[132:135], v[180:183], v[96:99]
	v_mfma_f32_16x16x32_bf16 v[92:95], v[140:143], v[180:183], v[92:95]
	v_mfma_f32_16x16x32_bf16 v[80:83], v[132:135], v[212:215], v[80:83]
	v_mfma_f32_16x16x32_bf16 v[76:79], v[140:143], v[212:215], v[76:79]
	v_mfma_f32_16x16x32_bf16 v[128:131], v[136:139], v[168:171], v[128:131]
	v_mfma_f32_16x16x32_bf16 v[124:127], v[144:147], v[168:171], v[124:127]
	v_mfma_f32_16x16x32_bf16 v[112:115], v[136:139], v[176:179], v[112:115]
	v_mfma_f32_16x16x32_bf16 v[108:111], v[144:147], v[176:179], v[108:111]
	v_mfma_f32_16x16x32_bf16 v[96:99], v[136:139], v[184:187], v[96:99]
	v_mfma_f32_16x16x32_bf16 v[92:95], v[144:147], v[184:187], v[92:95]
	v_mfma_f32_16x16x32_bf16 v[80:83], v[136:139], v[216:219], v[80:83]
	v_mfma_f32_16x16x32_bf16 v[76:79], v[144:147], v[216:219], v[76:79]
	s_setprio 0
	s_setprio 1
	v_mfma_f32_16x16x32_bf16 v[120:123], v[148:151], v[164:167], v[120:123]
	v_mfma_f32_16x16x32_bf16 v[116:119], v[156:159], v[164:167], v[116:119]
	v_mfma_f32_16x16x32_bf16 v[104:107], v[148:151], v[172:175], v[104:107]
	v_mfma_f32_16x16x32_bf16 v[100:103], v[156:159], v[172:175], v[100:103]
	v_mfma_f32_16x16x32_bf16 v[88:91], v[148:151], v[180:183], v[88:91]
	v_mfma_f32_16x16x32_bf16 v[84:87], v[156:159], v[180:183], v[84:87]
	v_mfma_f32_16x16x32_bf16 v[72:75], v[148:151], v[212:215], v[72:75]
	v_mfma_f32_16x16x32_bf16 v[68:71], v[156:159], v[212:215], v[68:71]
	v_mfma_f32_16x16x32_bf16 v[120:123], v[152:155], v[168:171], v[120:123]
	v_mfma_f32_16x16x32_bf16 v[116:119], v[160:163], v[168:171], v[116:119]
	v_mfma_f32_16x16x32_bf16 v[104:107], v[152:155], v[176:179], v[104:107]
	v_mfma_f32_16x16x32_bf16 v[100:103], v[160:163], v[176:179], v[100:103]
	v_mfma_f32_16x16x32_bf16 v[88:91], v[152:155], v[184:187], v[88:91]
	v_mfma_f32_16x16x32_bf16 v[84:87], v[160:163], v[184:187], v[84:87]
	v_mfma_f32_16x16x32_bf16 v[72:75], v[152:155], v[216:219], v[72:75]
	v_mfma_f32_16x16x32_bf16 v[68:71], v[160:163], v[216:219], v[68:71]
	s_setprio 0
	s_barrier
	s_add_i32 s30, s51, s34
	v_lshl_add_u64 v[6:7], v[228:229], 0, s[10:11]
	s_mov_b32 m0, s30
	ds_read_b128 v[164:167], v226 offset:49152
	ds_read_b128 v[168:171], v226 offset:50176
	ds_read_b128 v[172:175], v226 offset:51200
	ds_read_b128 v[176:179], v226 offset:52224
	ds_read_b128 v[180:183], v226 offset:53248
	ds_read_b128 v[184:187], v226 offset:54272
	ds_read_b128 v[212:215], v226 offset:55296
	ds_read_b128 v[216:219], v226 offset:56320
	global_load_lds_dwordx4 v[6:7], off
	s_add_i32 m0, s30, 0x2000
	s_add_u32 s28, s28, 0x40080
	v_lshl_add_u64 v[6:7], v[230:231], 0, s[10:11]
	s_addc_u32 s29, s29, 0
	s_add_i32 s30, s52, s34
	global_load_lds_dwordx4 v[6:7], off
	v_lshl_add_u64 v[6:7], s[28:29], 0, v[190:191]
	s_mov_b32 m0, s30
	s_nop 0
	global_load_lds_dwordx4 v[6:7], off
	v_lshl_add_u64 v[6:7], s[28:29], 0, v[194:195]
	s_add_i32 m0, s30, 0x2000
	s_nop 0
	global_load_lds_dwordx4 v[6:7], off
	v_lshl_add_u64 v[6:7], v[232:233], 0, s[10:11]
	s_mov_b32 m0, s40
	s_nop 0
	global_load_lds_dwordx4 v[6:7], off
	v_lshl_add_u64 v[6:7], v[234:235], 0, s[10:11]
	s_mov_b32 m0, s41
	s_nop 0
	global_load_lds_dwordx4 v[6:7], off
	s_waitcnt vmcnt(8)
	s_waitcnt lgkmcnt(0)
	s_barrier
	s_setprio 1
	s_waitcnt lgkmcnt(0)
	v_mfma_f32_16x16x32_bf16 v[64:67], v[132:135], v[164:167], v[64:67]
	v_mfma_f32_16x16x32_bf16 v[60:63], v[140:143], v[164:167], v[60:63]
	v_mfma_f32_16x16x32_bf16 v[48:51], v[132:135], v[172:175], v[48:51]
	v_mfma_f32_16x16x32_bf16 v[44:47], v[140:143], v[172:175], v[44:47]
	v_mfma_f32_16x16x32_bf16 v[32:35], v[132:135], v[180:183], v[32:35]
	v_mfma_f32_16x16x32_bf16 v[28:31], v[140:143], v[180:183], v[28:31]
	v_mfma_f32_16x16x32_bf16 v[16:19], v[132:135], v[212:215], v[16:19]
	v_mfma_f32_16x16x32_bf16 v[12:15], v[140:143], v[212:215], v[12:15]
	v_mfma_f32_16x16x32_bf16 v[64:67], v[136:139], v[168:171], v[64:67]
	v_mfma_f32_16x16x32_bf16 v[60:63], v[144:147], v[168:171], v[60:63]
	v_mfma_f32_16x16x32_bf16 v[48:51], v[136:139], v[176:179], v[48:51]
	v_mfma_f32_16x16x32_bf16 v[44:47], v[144:147], v[176:179], v[44:47]
	v_mfma_f32_16x16x32_bf16 v[32:35], v[136:139], v[184:187], v[32:35]
	v_mfma_f32_16x16x32_bf16 v[28:31], v[144:147], v[184:187], v[28:31]
	v_mfma_f32_16x16x32_bf16 v[16:19], v[136:139], v[216:219], v[16:19]
	v_mfma_f32_16x16x32_bf16 v[12:15], v[144:147], v[216:219], v[12:15]
	s_setprio 0
	s_setprio 1
	v_mfma_f32_16x16x32_bf16 v[56:59], v[148:151], v[164:167], v[56:59]
	v_mfma_f32_16x16x32_bf16 v[52:55], v[156:159], v[164:167], v[52:55]
	v_mfma_f32_16x16x32_bf16 v[40:43], v[148:151], v[172:175], v[40:43]
	v_mfma_f32_16x16x32_bf16 v[36:39], v[156:159], v[172:175], v[36:39]
	v_mfma_f32_16x16x32_bf16 v[24:27], v[148:151], v[180:183], v[24:27]
	v_mfma_f32_16x16x32_bf16 v[20:23], v[156:159], v[180:183], v[20:23]
	v_mfma_f32_16x16x32_bf16 v[6:9], v[148:151], v[212:215], v[8:11]
	v_mfma_f32_16x16x32_bf16 v[2:5], v[156:159], v[212:215], v[2:5]
	v_mfma_f32_16x16x32_bf16 v[56:59], v[152:155], v[168:171], v[56:59]
	v_mfma_f32_16x16x32_bf16 v[52:55], v[160:163], v[168:171], v[52:55]
	v_mfma_f32_16x16x32_bf16 v[40:43], v[152:155], v[176:179], v[40:43]
	v_mfma_f32_16x16x32_bf16 v[36:39], v[160:163], v[176:179], v[36:39]
	v_mfma_f32_16x16x32_bf16 v[24:27], v[152:155], v[184:187], v[24:27]
	v_mfma_f32_16x16x32_bf16 v[20:23], v[160:163], v[184:187], v[20:23]
	v_mfma_f32_16x16x32_bf16 v[8:11], v[152:155], v[216:219], v[6:9]
	v_mfma_f32_16x16x32_bf16 v[4:7], v[160:163], v[216:219], v[2:5]
	s_setprio 0
	s_barrier
	s_add_i32 s50, s50, 2
	s_add_u32 s26, s26, 0x100
	s_addc_u32 s27, s27, 0
	s_cmp_gt_u32 s50, 13
	s_cbranch_scc1 .LBB0_3844
